# top-k binary search: per-step count test done with a scalar compare instead of a 64-bit VALU compare + mask test (shorter serial chain)
# speedup vs baseline: 1.0165x; 1.0032x over previous
.LBB0_547:
	s_mov_b64 s[14:15], -1
	s_and_b64 vcc, exec, s[22:23]
	s_cbranch_vccz .LBB0_550
	ds_read_b32 v36, v37
	s_waitcnt lgkmcnt(0)
	v_max_f32_e32 v36, v36, v36
	v_max_f32_e32 v36, 0, v36
	v_add_u32_e32 v36, 1, v36
	v_cndmask_b32_e64 v36, v251, v36, s[10:11]
	v_cndmask_b32_e64 v36, 0, v36, s[6:7]
	v_cmp_lt_u32_e32 vcc, s3, v36
	s_bcnt1_i32_b64 s74, vcc
	s_cmp_gt_u32 s74, 15
	s_cselect_b32 s14, 2.0, 0
	s_or_b32 s15, s14, 0x20000000
	v_cmp_le_u32_e32 vcc, s15, v36
	s_bcnt1_i32_b64 s74, vcc
	s_cmp_gt_u32 s74, 15
	s_cselect_b32 s14, s15, s14
	s_or_b32 s15, s14, 0x10000000
	v_cmp_le_u32_e32 vcc, s15, v36
	s_bcnt1_i32_b64 s74, vcc
	s_cmp_gt_u32 s74, 15
	s_cselect_b32 s14, s15, s14
	s_or_b32 s15, s14, 0x8000000
	v_cmp_le_u32_e32 vcc, s15, v36
	s_bcnt1_i32_b64 s74, vcc
	s_cmp_gt_u32 s74, 15
	s_cselect_b32 s14, s15, s14
	s_or_b32 s15, s14, 0x4000000
	v_cmp_le_u32_e32 vcc, s15, v36
	s_bcnt1_i32_b64 s74, vcc
	s_cmp_gt_u32 s74, 15
	s_cselect_b32 s14, s15, s14
	s_or_b32 s15, s14, 0x2000000
	v_cmp_le_u32_e32 vcc, s15, v36
	s_bcnt1_i32_b64 s74, vcc
	s_cmp_gt_u32 s74, 15
	s_cselect_b32 s14, s15, s14
	s_or_b32 s15, s14, 0x1000000
	v_cmp_le_u32_e32 vcc, s15, v36
	s_bcnt1_i32_b64 s74, vcc
	s_cmp_gt_u32 s74, 15
	s_cselect_b32 s14, s15, s14
	s_or_b32 s15, s14, 0x800000
	v_cmp_le_u32_e32 vcc, s15, v36
	s_bcnt1_i32_b64 s74, vcc
	s_cmp_gt_u32 s74, 15
	s_cselect_b32 s14, s15, s14
	s_or_b32 s15, s14, 0x400000
	v_cmp_le_u32_e32 vcc, s15, v36
	s_bcnt1_i32_b64 s74, vcc
	s_cmp_gt_u32 s74, 15
	s_cselect_b32 s14, s15, s14
	s_or_b32 s15, s14, 0x200000
	v_cmp_le_u32_e32 vcc, s15, v36
	s_bcnt1_i32_b64 s74, vcc
	s_cmp_gt_u32 s74, 15
	s_cselect_b32 s14, s15, s14
	s_or_b32 s15, s14, 0x100000
	v_cmp_le_u32_e32 vcc, s15, v36
	s_bcnt1_i32_b64 s74, vcc
	s_cmp_gt_u32 s74, 15
	s_cselect_b32 s14, s15, s14
	s_or_b32 s15, s14, 0x80000
	v_cmp_le_u32_e32 vcc, s15, v36
	s_bcnt1_i32_b64 s74, vcc
	s_cmp_gt_u32 s74, 15
	s_cselect_b32 s14, s15, s14
	s_or_b32 s15, s14, 0x40000
	v_cmp_le_u32_e32 vcc, s15, v36
	s_bcnt1_i32_b64 s74, vcc
	s_cmp_gt_u32 s74, 15
	s_cselect_b32 s14, s15, s14
	s_or_b32 s15, s14, 0x20000
	v_cmp_le_u32_e32 vcc, s15, v36
	s_bcnt1_i32_b64 s74, vcc
	s_cmp_gt_u32 s74, 15
	s_cselect_b32 s14, s15, s14
	s_or_b32 s15, s14, 0x10000
	v_cmp_le_u32_e32 vcc, s15, v36
	s_bcnt1_i32_b64 s74, vcc
	s_cmp_gt_u32 s74, 15
	s_cselect_b32 s14, s15, s14
	s_or_b32 s15, s14, 0x8000
	v_cmp_le_u32_e32 vcc, s15, v36
	s_bcnt1_i32_b64 s74, vcc
	s_cmp_gt_u32 s74, 15
	s_cselect_b32 s14, s15, s14
	s_or_b32 s15, s14, 0x4000
	v_cmp_le_u32_e32 vcc, s15, v36
	s_bcnt1_i32_b64 s74, vcc
	s_cmp_gt_u32 s74, 15
	s_cselect_b32 s14, s15, s14
	s_or_b32 s15, s14, 0x2000
	v_cmp_le_u32_e32 vcc, s15, v36
	s_bcnt1_i32_b64 s74, vcc
	s_cmp_gt_u32 s74, 15
	s_cselect_b32 s14, s15, s14
	s_or_b32 s15, s14, 0x1000
	v_cmp_le_u32_e32 vcc, s15, v36
	s_bcnt1_i32_b64 s74, vcc
	s_cmp_gt_u32 s74, 15
	s_cselect_b32 s14, s15, s14
	s_or_b32 s15, s14, 0x800
	v_cmp_le_u32_e32 vcc, s15, v36
	s_bcnt1_i32_b64 s74, vcc
	s_cmp_gt_u32 s74, 15
	s_cselect_b32 s14, s15, s14
	s_or_b32 s15, s14, 0x400
	v_cmp_le_u32_e32 vcc, s15, v36
	s_bcnt1_i32_b64 s74, vcc
	s_cmp_gt_u32 s74, 15
	s_cselect_b32 s14, s15, s14
	s_or_b32 s15, s14, 0x200
	v_cmp_le_u32_e32 vcc, s15, v36
	s_bcnt1_i32_b64 s74, vcc
	s_cmp_gt_u32 s74, 15
	s_cselect_b32 s14, s15, s14
	s_or_b32 s15, s14, 0x100
	v_cmp_le_u32_e32 vcc, s15, v36
	s_bcnt1_i32_b64 s74, vcc
	s_cmp_gt_u32 s74, 15
	s_cselect_b32 s14, s15, s14
	s_or_b32 s15, s14, 0x80
	v_cmp_le_u32_e32 vcc, s15, v36
	s_bcnt1_i32_b64 s74, vcc
	s_cmp_gt_u32 s74, 15
	s_cselect_b32 s14, s15, s14
	s_or_b32 s15, s14, 64
	v_cmp_le_u32_e32 vcc, s15, v36
	s_bcnt1_i32_b64 s74, vcc
	s_cmp_gt_u32 s74, 15
	s_cselect_b32 s14, s15, s14
	s_or_b32 s15, s14, 32
	v_cmp_le_u32_e32 vcc, s15, v36
	s_bcnt1_i32_b64 s74, vcc
	s_cmp_gt_u32 s74, 15
	s_cselect_b32 s14, s15, s14
	s_or_b32 s15, s14, 16
	v_cmp_le_u32_e32 vcc, s15, v36
	s_bcnt1_i32_b64 s74, vcc
	s_cmp_gt_u32 s74, 15
	s_cselect_b32 s14, s15, s14
	s_or_b32 s15, s14, 8
	v_cmp_le_u32_e32 vcc, s15, v36
	s_bcnt1_i32_b64 s74, vcc
	s_cmp_gt_u32 s74, 15
	s_cselect_b32 s14, s15, s14
	s_or_b32 s15, s14, 4
	v_cmp_le_u32_e32 vcc, s15, v36
	s_bcnt1_i32_b64 s74, vcc
	s_cmp_gt_u32 s74, 15
	s_cselect_b32 s14, s15, s14
	s_or_b32 s15, s14, 2
	v_cmp_le_u32_e32 vcc, s15, v36
	s_bcnt1_i32_b64 s74, vcc
	s_cmp_gt_u32 s74, 15
	s_cselect_b32 s14, s15, s14
	s_or_b32 s15, s14, 1
	v_cmp_le_u32_e32 vcc, s15, v36
	s_bcnt1_i32_b64 s74, vcc
	s_cmp_gt_u32 s74, 15
	s_cselect_b32 s12, s15, s14
	v_cmp_lt_u32_e32 vcc, s12, v36
	v_cmp_eq_u32_e64 s[12:13], s12, v36
	s_bcnt1_i32_b64 s14, vcc
	s_sub_i32 s14, 16, s14
	v_and_b32_e32 v36, s12, v0
	v_and_b32_e32 v39, s13, v35
	v_bcnt_u32_b32 v36, v36, 0
	v_bcnt_u32_b32 v36, v39, v36
	v_cmp_gt_i32_e64 s[14:15], s14, v36
	s_and_b64 s[12:13], s[12:13], s[14:15]
	s_or_b64 s[12:13], vcc, s[12:13]
	v_cndmask_b32_e64 v36, 0, 1, s[12:13]
	v_cmp_ne_u32_e64 s[12:13], 0, v36
	v_cndmask_b32_e64 v36, 0, 1, s[6:7]
	s_cbranch_execz .LBB0_551

.LBB0_619:
	s_andn2_b64 vcc, exec, s[22:23]
	s_mov_b64 s[12:13], -1
	s_cbranch_vccnz .LBB0_622
	ds_read_b32 v2, v34
	s_waitcnt lgkmcnt(0)
	v_max_f32_e32 v2, v2, v2
	v_max_f32_e32 v2, 0, v2
	v_add_u32_e32 v2, 1, v2
	v_cndmask_b32_e64 v2, v251, v2, s[10:11]
	v_cndmask_b32_e64 v2, 0, v2, s[6:7]
	v_cmp_lt_u32_e32 vcc, s3, v2
	s_bcnt1_i32_b64 s74, vcc
	s_cmp_gt_u32 s74, 15
	s_cselect_b32 s12, 2.0, 0
	s_or_b32 s13, s12, 0x20000000
	v_cmp_le_u32_e32 vcc, s13, v2
	s_bcnt1_i32_b64 s74, vcc
	s_cmp_gt_u32 s74, 15
	s_cselect_b32 s12, s13, s12
	s_or_b32 s13, s12, 0x10000000
	v_cmp_le_u32_e32 vcc, s13, v2
	s_bcnt1_i32_b64 s74, vcc
	s_cmp_gt_u32 s74, 15
	s_cselect_b32 s12, s13, s12
	s_or_b32 s13, s12, 0x8000000
	v_cmp_le_u32_e32 vcc, s13, v2
	s_bcnt1_i32_b64 s74, vcc
	s_cmp_gt_u32 s74, 15
	s_cselect_b32 s12, s13, s12
	s_or_b32 s13, s12, 0x4000000
	v_cmp_le_u32_e32 vcc, s13, v2
	s_bcnt1_i32_b64 s74, vcc
	s_cmp_gt_u32 s74, 15
	s_cselect_b32 s12, s13, s12
	s_or_b32 s13, s12, 0x2000000
	v_cmp_le_u32_e32 vcc, s13, v2
	s_bcnt1_i32_b64 s74, vcc
	s_cmp_gt_u32 s74, 15
	s_cselect_b32 s12, s13, s12
	s_or_b32 s13, s12, 0x1000000
	v_cmp_le_u32_e32 vcc, s13, v2
	s_bcnt1_i32_b64 s74, vcc
	s_cmp_gt_u32 s74, 15
	s_cselect_b32 s12, s13, s12
	s_or_b32 s13, s12, 0x800000
	v_cmp_le_u32_e32 vcc, s13, v2
	s_bcnt1_i32_b64 s74, vcc
	s_cmp_gt_u32 s74, 15
	s_cselect_b32 s12, s13, s12
	s_or_b32 s13, s12, 0x400000
	v_cmp_le_u32_e32 vcc, s13, v2
	s_bcnt1_i32_b64 s74, vcc
	s_cmp_gt_u32 s74, 15
	s_cselect_b32 s12, s13, s12
	s_or_b32 s13, s12, 0x200000
	v_cmp_le_u32_e32 vcc, s13, v2
	s_bcnt1_i32_b64 s74, vcc
	s_cmp_gt_u32 s74, 15
	s_cselect_b32 s12, s13, s12
	s_or_b32 s13, s12, 0x100000
	v_cmp_le_u32_e32 vcc, s13, v2
	s_bcnt1_i32_b64 s74, vcc
	s_cmp_gt_u32 s74, 15
	s_cselect_b32 s12, s13, s12
	s_or_b32 s13, s12, 0x80000
	v_cmp_le_u32_e32 vcc, s13, v2
	s_bcnt1_i32_b64 s74, vcc
	s_cmp_gt_u32 s74, 15
	s_cselect_b32 s12, s13, s12
	s_or_b32 s13, s12, 0x40000
	v_cmp_le_u32_e32 vcc, s13, v2
	s_bcnt1_i32_b64 s74, vcc
	s_cmp_gt_u32 s74, 15
	s_cselect_b32 s12, s13, s12
	s_or_b32 s13, s12, 0x20000
	v_cmp_le_u32_e32 vcc, s13, v2
	s_bcnt1_i32_b64 s74, vcc
	s_cmp_gt_u32 s74, 15
	s_cselect_b32 s12, s13, s12
	s_or_b32 s13, s12, 0x10000
	v_cmp_le_u32_e32 vcc, s13, v2
	s_bcnt1_i32_b64 s74, vcc
	s_cmp_gt_u32 s74, 15
	s_cselect_b32 s12, s13, s12
	s_or_b32 s13, s12, 0x8000
	v_cmp_le_u32_e32 vcc, s13, v2
	s_bcnt1_i32_b64 s74, vcc
	s_cmp_gt_u32 s74, 15
	s_cselect_b32 s12, s13, s12
	s_or_b32 s13, s12, 0x4000
	v_cmp_le_u32_e32 vcc, s13, v2
	s_bcnt1_i32_b64 s74, vcc
	s_cmp_gt_u32 s74, 15
	s_cselect_b32 s12, s13, s12
	s_or_b32 s13, s12, 0x2000
	v_cmp_le_u32_e32 vcc, s13, v2
	s_bcnt1_i32_b64 s74, vcc
	s_cmp_gt_u32 s74, 15
	s_cselect_b32 s12, s13, s12
	s_or_b32 s13, s12, 0x1000
	v_cmp_le_u32_e32 vcc, s13, v2
	s_bcnt1_i32_b64 s74, vcc
	s_cmp_gt_u32 s74, 15
	s_cselect_b32 s12, s13, s12
	s_or_b32 s13, s12, 0x800
	v_cmp_le_u32_e32 vcc, s13, v2
	s_bcnt1_i32_b64 s74, vcc
	s_cmp_gt_u32 s74, 15
	s_cselect_b32 s12, s13, s12
	s_or_b32 s13, s12, 0x400
	v_cmp_le_u32_e32 vcc, s13, v2
	s_bcnt1_i32_b64 s74, vcc
	s_cmp_gt_u32 s74, 15
	s_cselect_b32 s12, s13, s12
	s_or_b32 s13, s12, 0x200
	v_cmp_le_u32_e32 vcc, s13, v2
	s_bcnt1_i32_b64 s74, vcc
	s_cmp_gt_u32 s74, 15
	s_cselect_b32 s12, s13, s12
	s_or_b32 s13, s12, 0x100
	v_cmp_le_u32_e32 vcc, s13, v2
	s_bcnt1_i32_b64 s74, vcc
	s_cmp_gt_u32 s74, 15
	s_cselect_b32 s12, s13, s12
	s_or_b32 s13, s12, 0x80
	v_cmp_le_u32_e32 vcc, s13, v2
	s_bcnt1_i32_b64 s74, vcc
	s_cmp_gt_u32 s74, 15
	s_cselect_b32 s12, s13, s12
	s_or_b32 s13, s12, 64
	v_cmp_le_u32_e32 vcc, s13, v2
	s_bcnt1_i32_b64 s74, vcc
	s_cmp_gt_u32 s74, 15
	s_cselect_b32 s12, s13, s12
	s_or_b32 s13, s12, 32
	v_cmp_le_u32_e32 vcc, s13, v2
	s_bcnt1_i32_b64 s74, vcc
	s_cmp_gt_u32 s74, 15
	s_cselect_b32 s12, s13, s12
	s_or_b32 s13, s12, 16
	v_cmp_le_u32_e32 vcc, s13, v2
	s_bcnt1_i32_b64 s74, vcc
	s_cmp_gt_u32 s74, 15
	s_cselect_b32 s12, s13, s12
	s_or_b32 s13, s12, 8
	v_cmp_le_u32_e32 vcc, s13, v2
	s_bcnt1_i32_b64 s74, vcc
	s_cmp_gt_u32 s74, 15
	s_cselect_b32 s12, s13, s12
	s_or_b32 s13, s12, 4
	v_cmp_le_u32_e32 vcc, s13, v2
	s_bcnt1_i32_b64 s74, vcc
	s_cmp_gt_u32 s74, 15
	s_cselect_b32 s12, s13, s12
	s_or_b32 s13, s12, 2
	v_cmp_le_u32_e32 vcc, s13, v2
	s_bcnt1_i32_b64 s74, vcc
	s_cmp_gt_u32 s74, 15
	s_cselect_b32 s12, s13, s12
	s_or_b32 s13, s12, 1
	v_cmp_le_u32_e32 vcc, s13, v2
	s_bcnt1_i32_b64 s74, vcc
	s_cmp_gt_u32 s74, 15
	s_cselect_b32 s4, s13, s12
	v_cmp_lt_u32_e32 vcc, s4, v2
	v_cmp_eq_u32_e64 s[4:5], s4, v2
	s_bcnt1_i32_b64 s12, vcc
	s_sub_i32 s12, 16, s12
	v_and_b32_e32 v2, s4, v0
	v_and_b32_e32 v3, s5, v35
	v_bcnt_u32_b32 v2, v2, 0
	v_bcnt_u32_b32 v2, v3, v2
	v_cmp_gt_i32_e64 s[12:13], s12, v2
	s_and_b64 s[4:5], s[4:5], s[12:13]
	s_or_b64 s[4:5], vcc, s[4:5]
	v_cndmask_b32_e64 v2, 0, 1, s[4:5]
	v_cmp_ne_u32_e64 s[4:5], 0, v2
	s_cbranch_execz .LBB0_623
